# natten: coalesced K loads staged through LDS + V prefetch issued mid-iteration; convert_p 8 loads in flight
# speedup vs baseline: 1.0020x; 1.0020x over previous
; __device__ __forceinline__ unsigned cvt_pk_bf16(float lo, float hi) { unsigned r; asm volatile("v_cvt_pk_bf16_f32 %0, %1, %2" : "=v"(r) : "v"(lo), "v"(hi)); return r; }
; __device__ __forceinline__ int otid() { int t = threadIdx.x; asm volatile("" : "+v"(t)); return t; }
; __device__ __forceinline__ float4 ntld_f4(const void* p) { const ntf4_t v = __builtin_nontemporal_load((const ntf4_t*)p); return make_float4(v.x, v.y, v.z, v.w); }
; __device__ void ph_convert_p(const float* __restrict__ p, bf16_t* __restrict__ pb) {
;     const size_t n4 = (size_t)T_TOK * PLE / 4;
;     for (size_t i = (size_t)blockIdx.x * NT + otid(); i < n4; i += (size_t)gridDim.x * NT) {
;         const float4 v = ntld_f4(((const float4*)p) + i); uint2 w; w.x = pg8::cvt_pk_bf16(v.x, v.y); w.y = pg8::cvt_pk_bf16(v.z, v.w); ((uint2*)pb)[i] = w; }
; }
.LBB0_38:
	v_mov_b32_e32 v4, v195
	v_readlane_b32 s0, v252, 56
	v_readlane_b32 s1, v252, 57
	v_ashrrev_i32_e32 v5, 31, v4
	s_waitcnt vmcnt(0)
	v_lshl_add_u64 v[0:1], s[0:1], 0, v[4:5]
	s_mov_b64 s[0:1], 0x200000
	v_cmp_gt_u64_e32 vcc, s[0:1], v[0:1]
	s_and_saveexec_b64 s[10:11], vcc
	s_cbranch_execz .LBB0_41
	v_readlane_b32 s0, v255, 5
	v_readlane_b32 s1, v255, 6
	s_mov_b64 s[14:15], 0
	s_nop 0
	v_lshl_add_u64 v[2:3], v[4:5], 4, s[0:1]
	v_readlane_b32 s0, v255, 8
	v_readlane_b32 s1, v255, 9
	s_nop 1
	v_lshl_add_u64 v[4:5], v[4:5], 3, s[0:1]
	s_lshl_b64 s[100:101], s[6:7], 3
	s_sub_u32 s100, s100, s6
	s_subb_u32 s101, s101, s7
	s_mov_b64 s[0:1], 0x1fffff
.Lcp8_loop:
	v_lshl_add_u64 v[10:11], v[0:1], 0, s[100:101]
	v_cmp_ge_u64_e32 vcc, s[0:1], v[10:11]
	s_cmp_eq_u64 vcc, exec
	s_cbranch_scc0 .LBB0_40
	global_load_dwordx4 v[6:9], v[2:3], off nt
	v_lshl_add_u64 v[2:3], v[2:3], 0, s[96:97]
	global_load_dwordx4 v[12:15], v[2:3], off nt
	v_lshl_add_u64 v[2:3], v[2:3], 0, s[96:97]
	global_load_dwordx4 v[40:43], v[2:3], off nt
	v_lshl_add_u64 v[2:3], v[2:3], 0, s[96:97]
	global_load_dwordx4 v[20:23], v[2:3], off nt
	v_lshl_add_u64 v[2:3], v[2:3], 0, s[96:97]
	global_load_dwordx4 v[24:27], v[2:3], off nt
	v_lshl_add_u64 v[2:3], v[2:3], 0, s[96:97]
	global_load_dwordx4 v[28:31], v[2:3], off nt
	v_lshl_add_u64 v[2:3], v[2:3], 0, s[96:97]
	global_load_dwordx4 v[32:35], v[2:3], off nt
	v_lshl_add_u64 v[2:3], v[2:3], 0, s[96:97]
	global_load_dwordx4 v[36:39], v[2:3], off nt
	v_lshl_add_u64 v[2:3], v[2:3], 0, s[96:97]
	v_lshl_add_u64 v[0:1], v[10:11], 0, s[6:7]
	s_waitcnt vmcnt(7)
	v_cvt_pk_bf16_f32 v6, v6, v7
	v_cvt_pk_bf16_f32 v7, v8, v9
	global_store_dwordx2 v[4:5], v[6:7], off
	v_lshl_add_u64 v[4:5], v[4:5], 0, s[60:61]
	s_waitcnt vmcnt(7)
	v_cvt_pk_bf16_f32 v12, v12, v13
	v_cvt_pk_bf16_f32 v13, v14, v15
	global_store_dwordx2 v[4:5], v[12:13], off
	v_lshl_add_u64 v[4:5], v[4:5], 0, s[60:61]
	s_waitcnt vmcnt(7)
	v_cvt_pk_bf16_f32 v40, v40, v41
	v_cvt_pk_bf16_f32 v41, v42, v43
	global_store_dwordx2 v[4:5], v[40:41], off
	v_lshl_add_u64 v[4:5], v[4:5], 0, s[60:61]
	s_waitcnt vmcnt(7)
	v_cvt_pk_bf16_f32 v20, v20, v21
	v_cvt_pk_bf16_f32 v21, v22, v23
	global_store_dwordx2 v[4:5], v[20:21], off
	v_lshl_add_u64 v[4:5], v[4:5], 0, s[60:61]
	s_waitcnt vmcnt(7)
	v_cvt_pk_bf16_f32 v24, v24, v25
	v_cvt_pk_bf16_f32 v25, v26, v27
	global_store_dwordx2 v[4:5], v[24:25], off
	v_lshl_add_u64 v[4:5], v[4:5], 0, s[60:61]
	s_waitcnt vmcnt(7)
	v_cvt_pk_bf16_f32 v28, v28, v29
	v_cvt_pk_bf16_f32 v29, v30, v31
	global_store_dwordx2 v[4:5], v[28:29], off
	v_lshl_add_u64 v[4:5], v[4:5], 0, s[60:61]
	s_waitcnt vmcnt(7)
	v_cvt_pk_bf16_f32 v32, v32, v33
	v_cvt_pk_bf16_f32 v33, v34, v35
	global_store_dwordx2 v[4:5], v[32:33], off
	v_lshl_add_u64 v[4:5], v[4:5], 0, s[60:61]
	s_waitcnt vmcnt(7)
	v_cvt_pk_bf16_f32 v36, v36, v37
	v_cvt_pk_bf16_f32 v37, v38, v39
	global_store_dwordx2 v[4:5], v[36:37], off
	v_lshl_add_u64 v[4:5], v[4:5], 0, s[60:61]
	v_cmp_ge_u64_e32 vcc, s[0:1], v[0:1]
	s_cmp_eq_u64 vcc, exec
	s_cbranch_scc1 .Lcp8_loop
	s_and_b64 exec, exec, vcc
	s_cbranch_execz .LBB0_41
